# S5 carry-scan loop: packed f32 ops on the serial chain split into scalar ops
# baseline (speedup 1.0000x reference)
.LBB0_298:
	v_cvt_pk_bf16_f32 v146, v122, s0
	v_cvt_pk_bf16_f32 v147, v123, s0
	v_mul_f32_e64 v132, v102, v122
	v_mul_f32_e64 v133, v103, v123
	v_mul_f32_e64 v122, v114, v122
	v_mul_f32_e64 v123, v115, v123
	s_add_i32 s1, s0, 8
	v_add_f32_e32 v122, v122, v123
	s_cmpk_lt_u32 s0, 0xf8
	v_sub_f32_e32 v132, v132, v133
	v_add_f32_e32 v122, v121, v122
	s_cselect_b64 s[8:9], -1, 0
	v_add_f32_e32 v120, v120, v132
	v_cvt_pk_bf16_f32 v149, v122, s0
	v_mul_f32_e64 v123, v115, v122
	v_mul_f32_e64 v122, v114, v122
	s_and_b64 vcc, s[8:9], exec
	v_cvt_pk_bf16_f32 v148, v120, s0
	v_fma_f32 v132, v102, v120, -v122
	v_fma_f32 v133, v103, v121, -v123
	v_fma_f32 v121, v103, v120, v123
	v_fma_f32 v120, v102, v120, v122
	s_cselect_b32 s8, s1, s0
	v_mov_b32_e32 v133, v121
	s_mov_b32 s0, s1
	v_lshl_add_u32 v144, s8, 9, v101
	v_add_f32_e64 v118, v118, v132
	v_add_f32_e64 v119, v119, v133
	ds_read2st64_b32 v[120:121], v144 offset1:1
	ds_read2st64_b32 v[122:123], v144 offset0:2 offset1:3
	ds_read2st64_b32 v[134:135], v144 offset0:4 offset1:5
	ds_read2st64_b32 v[136:137], v144 offset0:6 offset1:7
	ds_read2st64_b32 v[138:139], v144 offset0:8 offset1:9
	ds_read2st64_b32 v[140:141], v144 offset0:10 offset1:11
	ds_read2st64_b32 v[142:143], v144 offset0:12 offset1:13
	ds_read2st64_b32 v[144:145], v144 offset0:14 offset1:15
	s_waitcnt lgkmcnt(0)
	ds_write_b16 v131, v146
	ds_write_b16 v131, v147 offset:128
	ds_write_b16 v131, v148 offset:512
	ds_write_b16 v131, v149 offset:640
	v_cvt_pk_bf16_f32 v146, v118, s0
	v_cvt_pk_bf16_f32 v147, v119, s0
	v_mul_f32_e64 v132, v102, v118
	v_mul_f32_e64 v133, v103, v119
	v_pk_mul_f32 v[118:119], v[102:103], v[118:119] op_sel:[0,1] op_sel_hi:[1,0]
	v_sub_f32_e32 v132, v132, v133
	v_add_f32_e32 v118, v118, v119
	v_add_f32_e32 v110, v110, v132
	v_add_f32_e32 v118, v111, v118
	v_cvt_pk_bf16_f32 v111, v110, s0
	v_cvt_pk_bf16_f32 v132, v118, s0
	v_mul_f32_e64 v119, v103, v118
	v_mul_f32_e64 v118, v102, v118
	ds_write_b16 v131, v146 offset:1024
	ds_write_b16 v131, v147 offset:1152
	ds_write_b16 v131, v111 offset:1536
	ds_write_b16 v131, v132 offset:1664
	v_fma_f32 v132, v114, v110, v118
	v_fma_f32 v133, v115, v111, v119
	v_fma_f32 v146, v114, v110, -v118
	v_fma_f32 v147, v115, v110, -v119
	s_waitcnt lgkmcnt(14)
	v_mov_b32_e32 v118, v122
	v_mov_b32_e32 v133, v147
	v_mov_b32_e32 v119, v123
	v_add_f32_e64 v122, v116, v132
	v_add_f32_e64 v123, v117, v133
	s_waitcnt lgkmcnt(13)
	v_mov_b32_e32 v111, v135
	v_mov_b32_e32 v110, v134
	v_cvt_pk_bf16_f32 v134, v123, s0
	v_cvt_pk_bf16_f32 v135, v122, s0
	v_mul_f32_e64 v132, v102, v123
	v_mul_f32_e64 v133, v103, v122
	v_mul_f32_e64 v122, v102, v122
	v_mul_f32_e64 v123, v103, v123
	v_sub_f32_e32 v132, v132, v133
	v_add_f32_e32 v123, v122, v123
	v_add_f32_e32 v122, v104, v132
	v_add_f32_e32 v132, v105, v123
	ds_write_b16 v131, v134 offset:2048
	ds_write_b16 v131, v135 offset:2176
	v_cvt_pk_bf16_f32 v123, v122, s0
	v_cvt_pk_bf16_f32 v134, v132, s0
	v_mul_f32_e64 v133, v103, v132
	v_mul_f32_e64 v132, v102, v132
	ds_write_b16 v131, v123 offset:2560
	ds_write_b16 v131, v134 offset:2688
	v_fma_f32 v134, v114, v122, v132
	v_fma_f32 v135, v115, v123, v133
	v_fma_f32 v123, v115, v122, -v133
	v_fma_f32 v122, v114, v122, -v132
	s_waitcnt lgkmcnt(14)
	v_mov_b32_e32 v116, v137
	v_mov_b32_e32 v135, v123
	v_add_f32_e64 v122, v112, v134
	v_add_f32_e64 v123, v113, v135
	v_mov_b32_e32 v117, v136
	v_mul_f32_e64 v132, v102, v123
	v_mul_f32_e64 v133, v103, v122
	v_cvt_pk_bf16_f32 v134, v123, s0
	v_cvt_pk_bf16_f32 v135, v122, s0
	v_mul_f32_e64 v122, v102, v122
	v_mul_f32_e64 v123, v103, v123
	v_sub_f32_e32 v132, v132, v133
	v_add_f32_e32 v123, v122, v123
	v_add_f32_e32 v122, v106, v132
	v_add_f32_e32 v132, v107, v123
	v_cvt_pk_bf16_f32 v123, v122, s0
	ds_write_b16 v131, v134 offset:3072
	ds_write_b16 v131, v135 offset:3200
	v_cvt_pk_bf16_f32 v134, v132, s0
	v_mul_f32_e64 v133, v115, v132
	v_mul_f32_e64 v132, v114, v132
	ds_write_b16 v131, v123 offset:3584
	ds_write_b16 v131, v134 offset:3712
	v_fma_f32 v134, v102, v122, -v132
	v_fma_f32 v135, v103, v123, -v133
	v_fma_f32 v123, v103, v122, v133
	v_fma_f32 v122, v102, v122, v132
	v_mov_b32_e32 v105, v139
	v_mov_b32_e32 v135, v123
	v_mov_b32_e32 v104, v138
	v_mov_b32_e32 v112, v141
	v_mov_b32_e32 v113, v140
	s_waitcnt lgkmcnt(14)
	v_mov_b32_e32 v107, v143
	v_mov_b32_e32 v106, v142
	v_add_u32_e32 v131, 0x1000, v131
	v_add_f32_e64 v122, v108, v134
	v_add_f32_e64 v123, v109, v135
	v_mov_b32_e32 v108, v144
	v_mov_b32_e32 v109, v145
	s_cbranch_vccnz .LBB0_298
